# speedup vs baseline: 1.0029x; 1.0021x over previous
; __device__ __forceinline__ float bf2f(u16 h) { return __uint_as_float(((unsigned)h) << 16); }
; __device__ __forceinline__ void prep_load_new(PrepNew& N, const u16* PROJ, int r, int tid, unsigned zz) {
;   const u16* pr = PROJ + (long)r * NC;
;   N.c = make_uint4(zz, zz, zz, zz); N.sa = N.c; N.sc = N.c; N.sbv = N.c; N.dtr = 0.f;
;   if (tid < 384) N.c = *(const uint4*)(pr + OXBC + tid * 8);
;   else if (tid < 416) N.dtr = bf2f(pr[ODT + tid - 384]);
;   if (tid < 256) {
.LBB0_347:
	s_cmpk_lg_u32 s42, 0xe000
	s_cselect_b64 s[60:61], -1, 0
	s_cmpk_eq_u32 s42, 0xe000
	s_cbranch_scc1 .LBB0_358
	s_add_i32 s0, s48, s19
	s_mul_hi_i32 s1, s0, 0xba00
	s_mul_i32 s0, s0, 0xba00
	s_add_u32 s14, s35, s0
	s_addc_u32 s15, s58, s1
	s_and_saveexec_b64 s[0:1], s[6:7]
	s_xor_b64 s[0:1], exec, s[0:1]
	s_cbranch_execz .LBB0_352
	v_mov_b32_e32 v204, 0
	s_and_saveexec_b64 s[38:39], s[12:13]
	s_cbranch_execz .LBB0_351
	v_lshl_add_u64 v[12:13], v[2:3], 1, s[14:15]
	v_add_co_u32_e32 v12, vcc, 0xb000, v12
	s_nop 1
	v_addc_co_u32_e32 v13, vcc, 0, v13, vcc
	global_load_ushort v204, v[12:13], off offset:1280

; __device__ __forceinline__ void prep_compute(const PrepRegs& R, const PrepW& W, KP P, int l, int r, int b, int t, int tid, u16* PROJ, u16* XBC, float* DT, u16* ASC, bool dry) {
;     ...
;       {
;         const int e0 = tid * 8;
;         float x[8];
;         unpack8(qk, x);
;         float ss = 0.f;
; #pragma unroll
;         for (int i = 0; i < 8; ++i) ss += x[i] * x[i];
;         ss += sx<1>(ss); ss += sx<2>(ss); ss += sx<4>(ss); ss += sx<8>(ss);
;         const float rstd = rsqrtf(ss * (1.f / 128.f) + EPS);
;         const bool isK = e0 >= 2048;
;         const float* g = W.qg;
;         float y[8];
; #pragma unroll
;         for (int i = 0; i < 8; ++i) y[i] = x[i] * rstd * g[i];
;         if (!dry) *(uint4*)(pr + OQ + e0) = pack8(y);
;         if (isK && t >= 3584) {
;           float* dst = P->out + O_KP + ((long)(l * 2 + b) * 512 + (t - 3584)) * 2048 + (e0 - 2048);
; #pragma unroll
;           for (int i = 0; i < 8; ++i) dst[i] = y[i];
;         }
;       }
.LBB0_377:
	s_or_b64 exec, exec, s[14:15]
	s_cmp_lg_u32 s42, 0
	s_cbranch_scc1 .Lprep_nw
	s_waitcnt vmcnt(0)
.Lprep_nw:
	v_lshlrev_b32_e32 v80, 16, v76
	v_and_b32_e32 v81, 0xffff0000, v76
	v_pk_mul_f32 v[82:83], v[80:81], v[80:81]
	v_lshlrev_b32_e32 v86, 16, v77
	v_and_b32_e32 v87, 0xffff0000, v77
	v_pk_mul_f32 v[84:85], v[86:87], v[86:87]
	v_add_f32_e32 v82, v82, v83
	v_lshlrev_b32_e32 v196, 16, v78
	v_and_b32_e32 v197, 0xffff0000, v78
	v_add_f32_e32 v82, v84, v82
	v_pk_mul_f32 v[198:199], v[196:197], v[196:197]
	v_add_f32_e32 v82, v85, v82
	v_lshlrev_b32_e32 v200, 16, v79
	v_and_b32_e32 v201, 0xffff0000, v79
	v_add_f32_e32 v82, v198, v82
	v_pk_mul_f32 v[206:207], v[200:201], v[200:201]
	v_add_f32_e32 v82, v199, v82
	v_add_f32_e32 v82, v206, v82
	v_add_f32_e32 v82, v207, v82
	ds_swizzle_b32 v83, v82 offset:swizzle(SWAP,1)
	s_add_u32 s0, s49, s22
	s_addc_u32 s1, s50, s23
	s_cmpk_gt_u32 s38, 0xdff
	v_lshl_add_u64 v[88:89], s[0:1], 0, v[88:89]
	s_waitcnt lgkmcnt(0)
	v_add_f32_e32 v82, v82, v83
	ds_swizzle_b32 v83, v82 offset:swizzle(SWAP,2)
	s_cselect_b64 s[0:1], -1, 0
	s_and_b64 s[14:15], s[4:5], s[0:1]
	s_waitcnt lgkmcnt(0)
	v_add_f32_e32 v82, v82, v83
	ds_swizzle_b32 v83, v82 offset:swizzle(SWAP,4)
	s_waitcnt lgkmcnt(0)
	v_add_f32_e32 v82, v82, v83
	ds_swizzle_b32 v83, v82 offset:swizzle(SWAP,8)
	s_waitcnt lgkmcnt(0)
	v_add_f32_e32 v82, v82, v83
	v_fmamk_f32 v82, v82, 0x3c000000, v189
	v_cmp_gt_f32_e32 vcc, s62, v82
	v_mul_f32_e32 v83, 0x4b800000, v82
	s_nop 0
	v_cndmask_b32_e32 v82, v82, v83, vcc
	v_rsq_f32_e32 v82, v82
	s_nop 0
	v_mul_f32_e32 v83, 0x45800000, v82
	v_cndmask_b32_e32 v82, v82, v83, vcc
	v_pk_mul_f32 v[80:81], v[82:83], v[80:81] op_sel_hi:[0,1]
	v_pk_mul_f32 v[84:85], v[110:111], v[80:81]
	v_pk_mul_f32 v[80:81], v[82:83], v[86:87] op_sel_hi:[0,1]
	v_pk_mul_f32 v[86:87], v[128:129], v[80:81]
	v_pk_mul_f32 v[80:81], v[82:83], v[196:197] op_sel_hi:[0,1]
	v_and_b32_sdwa v197, v84, v226 dst_sel:DWORD dst_unused:UNUSED_PAD src0_sel:WORD_1 src1_sel:DWORD
	v_add3_u32 v198, v84, v197, s33
	v_and_b32_sdwa v197, v87, v226 dst_sel:DWORD dst_unused:UNUSED_PAD src0_sel:WORD_1 src1_sel:DWORD
	v_and_b32_sdwa v199, v85, v226 dst_sel:DWORD dst_unused:UNUSED_PAD src0_sel:WORD_1 src1_sel:DWORD
	v_and_b32_sdwa v196, v86, v226 dst_sel:DWORD dst_unused:UNUSED_PAD src0_sel:WORD_1 src1_sel:DWORD
	v_add3_u32 v197, v87, v197, s33
	v_add3_u32 v199, v85, v199, s33
	v_pk_mul_f32 v[80:81], v[146:147], v[80:81]
	v_pk_mul_f32 v[82:83], v[82:83], v[200:201] op_sel_hi:[0,1]
	v_add3_u32 v196, v86, v196, s33
	v_and_b32_e32 v197, 0xffff0000, v197
	v_and_b32_e32 v199, 0xffff0000, v199
	v_pk_mul_f32 v[82:83], v[164:165], v[82:83]
	v_or_b32_sdwa v197, v197, v196 dst_sel:DWORD dst_unused:UNUSED_PAD src0_sel:DWORD src1_sel:WORD_1
	v_or_b32_sdwa v196, v199, v198 dst_sel:DWORD dst_unused:UNUSED_PAD src0_sel:DWORD src1_sel:WORD_1
	v_and_b32_sdwa v199, v80, v226 dst_sel:DWORD dst_unused:UNUSED_PAD src0_sel:WORD_1 src1_sel:DWORD
	v_add3_u32 v200, v80, v199, s33
	v_and_b32_sdwa v199, v83, v226 dst_sel:DWORD dst_unused:UNUSED_PAD src0_sel:WORD_1 src1_sel:DWORD
	v_and_b32_sdwa v201, v81, v226 dst_sel:DWORD dst_unused:UNUSED_PAD src0_sel:WORD_1 src1_sel:DWORD
	v_and_b32_sdwa v198, v82, v226 dst_sel:DWORD dst_unused:UNUSED_PAD src0_sel:WORD_1 src1_sel:DWORD
	v_add3_u32 v199, v83, v199, s33
	v_add3_u32 v201, v81, v201, s33
	v_add3_u32 v198, v82, v198, s33
	v_and_b32_e32 v199, 0xffff0000, v199
	v_and_b32_e32 v201, 0xffff0000, v201
	v_or_b32_sdwa v199, v199, v198 dst_sel:DWORD dst_unused:UNUSED_PAD src0_sel:DWORD src1_sel:WORD_1
	v_or_b32_sdwa v198, v201, v200 dst_sel:DWORD dst_unused:UNUSED_PAD src0_sel:DWORD src1_sel:WORD_1
	global_store_dwordx4 v[88:89], v[196:199], off offset:-8
	s_and_saveexec_b64 s[0:1], s[14:15]
	s_cbranch_execz .LBB0_379
	s_load_dwordx2 s[14:15], s[20:21], 0xd0
	s_waitcnt lgkmcnt(0)
	v_lshl_add_u64 v[88:89], s[14:15], 0, v[192:193]
	v_lshl_add_u64 v[88:89], v[88:89], 0, s[42:43]
	v_add_co_u32_e32 v88, vcc, 0x40fe000, v88
	s_nop 1
	v_addc_co_u32_e32 v89, vcc, 0, v89, vcc
	global_store_dwordx4 v[88:89], v[84:87], off
	global_store_dwordx4 v[88:89], v[80:83], off offset:16
.LBB0_379:
	s_or_b64 exec, exec, s[0:1]
	s_andn2_b64 vcc, exec, s[60:61]
	s_cbranch_vccnz .LBB0_346
	s_waitcnt vmcnt(1)
	v_mov_b64_e32 v[28:29], v[36:37]
	v_mov_b64_e32 v[30:31], v[38:39]
	v_mov_b64_e32 v[36:37], v[40:41]
	v_mov_b64_e32 v[48:49], v[56:57]
	v_mov_b64_e32 v[52:53], v[60:61]
	v_mov_b64_e32 v[38:39], v[42:43]
	v_mov_b64_e32 v[40:41], v[44:45]
	v_mov_b64_e32 v[50:51], v[58:59]
	v_mov_b64_e32 v[56:57], v[68:69]
	v_mov_b64_e32 v[54:55], v[62:63]
	v_mov_b64_e32 v[60:61], v[64:65]
	v_mov_b64_e32 v[42:43], v[46:47]
	v_mov_b64_e32 v[46:47], v[14:15]
	v_mov_b64_e32 v[58:59], v[70:71]
	v_mov_b64_e32 v[70:71], v[18:19]
	v_mov_b64_e32 v[62:63], v[66:67]
	v_mov_b64_e32 v[66:67], v[22:23]
	v_mov_b64_e32 v[78:79], v[34:35]
	v_mov_b64_e32 v[74:75], v[26:27]
	v_mov_b64_e32 v[44:45], v[12:13]
	v_mov_b64_e32 v[68:69], v[16:17]
	v_mov_b64_e32 v[64:65], v[20:21]
	v_lshlrev_b32_e32 v205, 16, v204
	v_mov_b64_e32 v[76:77], v[32:33]
	v_mov_b64_e32 v[72:73], v[24:25]
	s_branch .LBB0_346
